# code placement: GEMM phase code (and what follows) shifted by 4 bytes, NA and MLA phases kept (on v37)
# speedup vs baseline: 1.0856x; 1.0856x over previous
; __global__ void __launch_bounds__(NWAVES * 64, 2) fwd_mega(Args args) {
;     ...
;         } else if (EN_GEMM && kind == 1) {
;             const int ng = (is_mla && sub == 2) ? 2 : 1;
;             for (int gi = 0; gi < ng * REP_GEMM; ++gi) {
;                 const bf16_t* A; const bf16_t* Bt; bf16_t* O; int N, K;
;                 if (!is_mla) { if (sub == 0) { A = H; Bt = A_WIN; O = QKVZ; N = NA_N; K = DM; } else { A = H; Bt = A_WOUT; O = Y; N = DM; K = DM; } }
;                 else { if (sub == 0) { A = H; Bt = (layer == 3) ? B_WIN2 : B_WIN; O = WINO; N = MLA_NP; K = DM; }
;                        else if (sub == 2) { if ((gi % ng) == 0) { A = CQN; Bt = B_WQB; O = QB; N = QB_N; K = LORA; } else { A = CKVN; Bt = B_WKVB; O = KVB; N = KVB_N; K = LORA; } }
;                        else { A = H; Bt = B_WOUT; O = Y; N = DM; K = DM; } }
;                 pg8::Gemm g{A, Bt, M_TOK, N, K}; pg8::StaticOrder S; S.init(M_TOK, N, G, bx);
;                 const bool tm_ = !(is_mla && sub == 2 && (gi % ng) == 0);
;                 pg8::EpiBf16<0> E{O, tm_ ? 256 : N, nullptr, tm_ ? 256 : 0, tm_ ? (size_t)M_TOK * 256 : (size_t)0, 1.f};
.LBB0_353:
	s_nop 0
	s_andn2_b64 vcc, exec, s[6:7]
	s_mov_b32 s0, -1
	s_cbranch_vccnz .LBB0_385
	s_and_b32 s0, 0xffff, s49
	s_cmp_gt_i32 s0, 0
	s_mov_b32 s0, -1
	s_cbranch_scc0 .LBB0_385
	s_add_u32 s1, s45, 0x1d000000
	s_addc_u32 s5, s68, 0
	s_mov_b32 s13, s62
	s_add_u32 s62, s45, 0x1e000000
	s_addc_u32 s16, s68, 0
	s_bitcmp1_b32 s48, 0
	s_cselect_b64 s[34:35], -1, 0
	s_add_u32 s10, s45, 0x2c00000
	s_addc_u32 s12, s68, 0
	s_lshl_b64 s[6:7], 1, s61
	s_and_b32 s36, s6, 0x22088
	s_mov_b32 s37, 0
	s_cmp_lg_u64 s[36:37], 0
	s_cselect_b64 s[42:43], -1, 0
	s_and_b64 s[46:47], s[34:35], s[42:43]
	s_and_b64 s[8:9], s[46:47], exec
	s_cselect_b32 s17, 2, 1
	s_add_i32 s18, s17, -1
	s_and_b32 s36, s6, 0x8823
	s_cmp_eq_u64 s[36:37], 0
	s_cselect_b64 s[50:51], -1, 0
	s_and_b64 s[6:7], s[50:51], exec
	s_movk_i32 s6, 0x800
	s_cselect_b32 s19, s6, 0x2000
	v_readlane_b32 s6, v254, 48
	v_readlane_b32 s8, v254, 50
	v_readlane_b32 s7, v254, 49
	v_readlane_b32 s9, v254, 51
	s_cselect_b32 s39, s9, s7
	s_cselect_b32 s38, s8, s6
	s_add_u32 s6, s61, -15
	s_addc_u32 s7, s44, -1
	v_cmp_lt_u64_e64 s[6:7], s[6:7], 6
	s_and_b64 s[6:7], s[6:7], exec
	v_readlane_b32 s6, v254, 52
	v_readlane_b32 s7, v254, 53
	s_cselect_b32 s65, s7, s12
	s_cselect_b32 s64, s6, s10
	s_cmp_lg_u64 s[36:37], 0
	s_cselect_b64 s[6:7], -1, 0
	s_and_b64 s[78:79], s[34:35], s[6:7]
	s_add_u32 s6, s61, -5
	s_addc_u32 s7, s44, -1
	v_cmp_lt_u64_e64 s[6:7], s[6:7], 6
	s_and_b64 s[6:7], s[6:7], exec
	v_writelane_b32 v255, s61, 14
	v_readlane_b32 s6, v253, 62
	s_mov_b32 s33, s52
	s_cselect_b32 s36, 0, 2
	v_writelane_b32 v255, s13, 15
	s_add_i32 s24, s13, s6
	s_waitcnt vmcnt(0)
	s_branch .LBB0_357
